# H2 hand-written loader/compute split; H2 workgroup-to-(b,h) mapping spreads heads over XCDs (4 heads per XCD, both v-halves co-located); unit-start vmcnt(0) removed in 7 GEMM bodies
# baseline (speedup 1.0000x reference)
; #define LAS __attribute__((address_space(3)))
; #define H2_PRIV(cc, VT_, OI_) do { const int tok0_ = b * T + 64 * (cc); \
;         const bf16* vp_ = Z2 + (size_t)(tok0_ + (vcol >> 1)) * NH2 + 2048 + h * 128 + (vcol & 1) * 64 + 8 * fq; VT_[0] = *(const u32x4*)vp_; VT_[1] = *(const u32x4*)(vp_ + 32); \
;         _Pragma("unroll") for (int tt_ = 0; tt_ < 4; ++tt_) OI_[tt_] = OI[((size_t)((unit0 + (cc)) * 4 + tt_) * 8 + w) * 64 + lane]; } while (0)
; template <bool DRY> DI void hgrn2_phase(LAS unsigned char* L, bf16* Z2, const float* DEC, unsigned long long* OIW, int bh2, int tid) {
;     const unsigned long long* OI = OIW;
;     const int wv = __builtin_amdgcn_readfirstlane(tid >> 6), lane = tid & 63, fr = lane & 15, fq = lane >> 4;
;     const int bh = bh2 >> 1, w = 4 * (bh2 & 1) + (wv & 3); const bool cw = wv < 4;
;     const int b = bh >> 3, h = bh & 7, unit0 = bh * 64, vcol = 16 * w + fr;
;     u32x4 sqA[2], skA[2]; f32x4 sdA = (f32x4){0.f, 0.f, 0.f, 0.f};
;     ...
;     u32x4 vtf[2] = {(u32x4){0u, 0u, 0u, 0u}, (u32x4){0u, 0u, 0u, 0u}}; unsigned long long oi[4] = {0ull, 0ull, 0ull, 0ull};
;     u32x4 nvt[2] = {(u32x4){0u, 0u, 0u, 0u}, (u32x4){0u, 0u, 0u, 0u}}; unsigned long long noi[4] = {0ull, 0ull, 0ull, 0ull};
;     H2_LOAD(0, sqA, skA, sdA); H2_WRITE(0, sqA, skA, sdA); if (cw) H2_PRIV(0, vtf, oi);
;     H2_LOAD(1, sqA, skA, sdA); if (cw) H2_PRIV(1, nvt, noi);
;     f32x4 S[8];
; #pragma unroll
;     for (int nt = 0; nt < 8; ++nt) S[nt] = (f32x4){0.f, 0.f, 0.f, 0.f};
;     __syncthreads();
.LBB0_686:
	s_and_b64 vcc, exec, s[2:3]
	s_cbranch_vccz .LBB0_713
	s_and_b32 s39, s26, 7
	s_lshr_b32 s42, s26, 3
	s_lshr_b32 s38, s39, 1
	s_lshl_b32 s38, s38, 3
	s_and_b32 s43, s39, 1
	s_lshl_b32 s43, s43, 2
	s_or_b32 s38, s38, s43
	s_and_b32 s43, s42, 3
	s_or_b32 s38, s38, s43
	s_lshr_b32 s39, s42, 2
	s_lshr_b32 s40, s38, 3
	s_and_b32 s41, s38, 7
	s_lshl_b32 s42, s40, 25
	s_lshl_b32 s43, s41, 8
	s_add_u32 s42, s42, s43
	s_add_u32 s42, s42, 0x6400000
	s_add_u32 s44, s9, s42
	s_addc_u32 s45, s14, 0
	s_lshl_b32 s42, s38, 15
	s_add_u32 s42, s42, 0x14500000
	s_add_u32 s46, s9, s42
	s_addc_u32 s47, s14, 0
	s_lshl_b32 s42, s38, 20
	s_add_u32 s42, s42, 0xf400000
	s_add_u32 s48, s9, s42
	s_addc_u32 s49, s14, 0
	v_readfirstlane_b32 s50, v131
	s_nop 3
	s_lshr_b32 s50, s50, 6
	s_cmp_ge_u32 s50, 4
	s_cbranch_scc1 .Lh2_loader
	s_lshl_b32 s51, s39, 2
	s_add_u32 s51, s51, s50
	v_and_b32_e32 v207, 15, v130
	v_lshrrev_b32_e32 v208, 4, v130
	v_mul_u32_u24_e32 v190, 0x110, v207
	v_lshl_add_u32 v190, v208, 3, v190
	v_mul_u32_u24_e32 v191, 0x90, v207
	v_lshl_add_u32 v191, v208, 4, v191
	v_lshlrev_b32_e32 v192, 4, v208
	s_lshl_b32 s42, s50, 11
	v_lshlrev_b32_e32 v193, 4, v130
	v_add_u32_e32 v193, s42, v193
	v_lshlrev_b32_e32 v194, 3, v130
	v_add_u32_e32 v194, s42, v194
	s_lshl_b32 s43, s51, 9
	v_lshlrev_b32_e32 v195, 3, v130
	v_add_u32_e32 v195, s43, v195
	v_add_u32_e32 v206, 0x3000, v195
	v_add_u32_e32 v195, 0x1000, v195
	v_mov_b32_e32 v10, 0
	v_mov_b32_e32 v11, 0
	v_mov_b32_e32 v12, 0
	v_mov_b32_e32 v13, 0
	v_mov_b32_e32 v14, 0
	v_mov_b32_e32 v15, 0
	v_mov_b32_e32 v16, 0
	v_mov_b32_e32 v17, 0
	v_mov_b32_e32 v18, 0
	v_mov_b32_e32 v19, 0
	v_mov_b32_e32 v20, 0
	v_mov_b32_e32 v21, 0
	v_mov_b32_e32 v22, 0
	v_mov_b32_e32 v23, 0
	v_mov_b32_e32 v24, 0
	v_mov_b32_e32 v25, 0
	v_mov_b32_e32 v26, 0
	v_mov_b32_e32 v27, 0
	v_mov_b32_e32 v28, 0
	v_mov_b32_e32 v29, 0
	v_mov_b32_e32 v30, 0
	v_mov_b32_e32 v31, 0
	v_mov_b32_e32 v32, 0
	v_mov_b32_e32 v33, 0
	v_mov_b32_e32 v34, 0
	v_mov_b32_e32 v35, 0
	v_mov_b32_e32 v36, 0
	v_mov_b32_e32 v37, 0
	v_mov_b32_e32 v38, 0
	v_mov_b32_e32 v39, 0
	v_mov_b32_e32 v40, 0
	v_mov_b32_e32 v41, 0
	s_mov_b32 s52, 0
	s_mov_b32 s53, 0
	s_mov_b32 s54, s48
	s_mov_b32 s55, s49
	v_add_u32_e32 v2, s52, v190
	v_add_u32_e32 v3, 0x1000, v2
	v_add_u32_e32 v4, 0x2000, v2
	v_add_u32_e32 v5, 0x3000, v2
	v_add_u32_e32 v6, s52, v191
	v_add_u32_e32 v7, s52, v192
	v_add_u32_e32 v8, s52, v193
	v_add_u32_e32 v9, s52, v194
	v_cvt_pk_bf16_f32 v42, v10, v11
	v_cvt_pk_bf16_f32 v43, v12, v13
	v_cvt_pk_bf16_f32 v44, v14, v15
	v_cvt_pk_bf16_f32 v45, v16, v17
	v_cvt_pk_bf16_f32 v46, v18, v19
	v_cvt_pk_bf16_f32 v47, v20, v21
	v_cvt_pk_bf16_f32 v48, v22, v23
	v_cvt_pk_bf16_f32 v49, v24, v25
	v_cvt_pk_bf16_f32 v50, v26, v27
	v_cvt_pk_bf16_f32 v51, v28, v29
	v_cvt_pk_bf16_f32 v52, v30, v31
	v_cvt_pk_bf16_f32 v53, v32, v33
	v_cvt_pk_bf16_f32 v54, v34, v35
	v_cvt_pk_bf16_f32 v55, v36, v37
	v_cvt_pk_bf16_f32 v56, v38, v39
	v_cvt_pk_bf16_f32 v57, v40, v41
	s_barrier
